# RWKV-7 scan: consumer waves run their serial state-update block at s_setprio 3 so the co-resident producer wave of the same SIMD yields VALU issue slots
# speedup vs baseline: 1.0021x; 1.0021x over previous
.LBB0_171:
	s_andn2_b64 vcc, exec, s[36:37]
	s_cbranch_vccnz .LBB0_175
	s_setprio 3
	v_add_u32_e32 v145, s29, v63
	v_add_u32_e32 v145, 0x1000, v145
	ds_read2_b32 v[154:155], v145 offset0:0 offset1:32
	ds_read2_b32 v[156:157], v145 offset0:64 offset1:96
	ds_read2_b32 v[158:159], v145 offset0:128 offset1:160
	ds_read2_b32 v[238:239], v145 offset0:192 offset1:224
	ds_read_b128 v[176:179], v118 offset:24576
	ds_read_b128 v[180:183], v118 offset:24592
	ds_read_b128 v[206:209], v118 offset:16384
	ds_read_b128 v[210:213], v118 offset:16400
	ds_read_b128 v[192:195], v118 offset:8192
	ds_read_b128 v[196:199], v118 offset:8208
	ds_read_b128 v[184:187], v118 offset:32768
	ds_read_b128 v[188:191], v118 offset:32784
	ds_read_b128 v[214:217], v118 offset:0
	ds_read_b128 v[218:221], v118 offset:16
	v_add_u32_e32 v240, s29, v117
	v_add_u32_e32 v240, 0x17000, v240
	s_waitcnt lgkmcnt(6)
	v_pk_mul_f32 v[30:31], v[206:207], v[154:155] op_sel_hi:[1,0]
	v_pk_mul_f32 v[32:33], v[208:209], v[154:155] op_sel_hi:[1,0]
	v_pk_mul_f32 v[34:35], v[210:211], v[154:155] op_sel_hi:[1,0]
	v_pk_mul_f32 v[36:37], v[212:213], v[154:155] op_sel_hi:[1,0]
	v_pk_mul_f32 v[38:39], v[84:85], v[176:177]
	v_pk_fma_f32 v[38:39], v[86:87], v[178:179], v[38:39]
	v_pk_fma_f32 v[38:39], v[88:89], v[180:181], v[38:39]
	v_pk_fma_f32 v[38:39], v[90:91], v[182:183], v[38:39]
	ds_read_b128 v[222:225], v118 offset:24832
	ds_read_b128 v[226:229], v118 offset:24848
	v_add_f32_e32 v42, v38, v39
	s_waitcnt lgkmcnt(7)
	v_pk_fma_f32 v[30:31], v[84:85], v[192:193], v[30:31]
	ds_read_b128 v[130:133], v118 offset:16640
	v_add_f32_dpp v42, v42, v42 quad_perm:[1,0,3,2] row_mask:0xf bank_mask:0xf bound_ctrl:1
	v_pk_fma_f32 v[32:33], v[86:87], v[194:195], v[32:33]
	ds_read_b128 v[134:137], v118 offset:16656
	v_add_f32_dpp v42, v42, v42 quad_perm:[2,3,0,1] row_mask:0xf bank_mask:0xf bound_ctrl:1
	s_waitcnt lgkmcnt(8)
	v_pk_fma_f32 v[34:35], v[88:89], v[196:197], v[34:35]
	ds_read_b128 v[122:125], v118 offset:8448
	v_add_f32_dpp v42, v42, v42 row_half_mirror row_mask:0xf bank_mask:0xf bound_ctrl:1
	v_pk_fma_f32 v[36:37], v[90:91], v[198:199], v[36:37]
	ds_read_b128 v[126:129], v118 offset:8464
	ds_read_b128 v[230:233], v118 offset:33024
	s_waitcnt lgkmcnt(10)
	v_pk_fma_f32 v[84:85], v[184:185], v[42:43], v[30:31] op_sel_hi:[1,0,1]
	v_pk_fma_f32 v[86:87], v[186:187], v[42:43], v[32:33] op_sel_hi:[1,0,1]
	s_waitcnt lgkmcnt(9)
	v_pk_fma_f32 v[88:89], v[188:189], v[42:43], v[34:35] op_sel_hi:[1,0,1]
	v_pk_fma_f32 v[90:91], v[190:191], v[42:43], v[36:37] op_sel_hi:[1,0,1]
	ds_read_b128 v[234:237], v118 offset:33040
	ds_read_b128 v[146:149], v118 offset:256
	ds_read_b128 v[150:153], v118 offset:272
	s_waitcnt lgkmcnt(6)
	v_pk_mul_f32 v[30:31], v[130:131], v[154:155] op_sel:[0,1]
	v_pk_mul_f32 v[32:33], v[132:133], v[154:155] op_sel:[0,1]
	v_pk_mul_f32 v[34:35], v[134:135], v[154:155] op_sel:[0,1]
	v_pk_mul_f32 v[36:37], v[136:137], v[154:155] op_sel:[0,1]
	v_pk_mul_f32 v[38:39], v[84:85], v[222:223]
	v_pk_mul_f32 v[40:41], v[84:85], v[214:215]
	v_pk_fma_f32 v[38:39], v[86:87], v[224:225], v[38:39]
	v_pk_fma_f32 v[40:41], v[86:87], v[216:217], v[40:41]
	v_pk_fma_f32 v[38:39], v[88:89], v[226:227], v[38:39]
	v_pk_fma_f32 v[40:41], v[88:89], v[218:219], v[40:41]
	v_pk_fma_f32 v[38:39], v[90:91], v[228:229], v[38:39]
	v_pk_fma_f32 v[40:41], v[90:91], v[220:221], v[40:41]
	ds_read_b128 v[176:179], v118 offset:25088
	ds_read_b128 v[180:183], v118 offset:25104
	v_add_f32_e32 v42, v38, v39
	v_add_f32_e32 v44, v40, v41
	s_waitcnt lgkmcnt(7)
	v_pk_fma_f32 v[30:31], v[84:85], v[122:123], v[30:31]
	v_add_f32_dpp v42, v42, v42 quad_perm:[1,0,3,2] row_mask:0xf bank_mask:0xf bound_ctrl:1
	v_add_f32_dpp v44, v44, v44 quad_perm:[1,0,3,2] row_mask:0xf bank_mask:0xf bound_ctrl:1
	v_pk_fma_f32 v[32:33], v[86:87], v[124:125], v[32:33]
	v_add_f32_dpp v42, v42, v42 quad_perm:[2,3,0,1] row_mask:0xf bank_mask:0xf bound_ctrl:1
	v_add_f32_dpp v44, v44, v44 quad_perm:[2,3,0,1] row_mask:0xf bank_mask:0xf bound_ctrl:1
	s_waitcnt lgkmcnt(6)
	v_pk_fma_f32 v[34:35], v[88:89], v[126:127], v[34:35]
	v_add_f32_dpp v42, v42, v42 row_half_mirror row_mask:0xf bank_mask:0xf bound_ctrl:1
	v_add_f32_dpp v45, v44, v44 row_half_mirror row_mask:0xf bank_mask:0xf bound_ctrl:1
	v_pk_fma_f32 v[36:37], v[90:91], v[128:129], v[36:37]
	ds_read_b128 v[206:209], v118 offset:16896
	ds_read_b128 v[210:213], v118 offset:16912
	s_waitcnt lgkmcnt(7)
	v_pk_fma_f32 v[84:85], v[230:231], v[42:43], v[30:31] op_sel_hi:[1,0,1]
	v_pk_fma_f32 v[86:87], v[232:233], v[42:43], v[32:33] op_sel_hi:[1,0,1]
	s_waitcnt lgkmcnt(6)
	v_pk_fma_f32 v[88:89], v[234:235], v[42:43], v[34:35] op_sel_hi:[1,0,1]
	v_pk_fma_f32 v[90:91], v[236:237], v[42:43], v[36:37] op_sel_hi:[1,0,1]
	ds_read_b128 v[192:195], v118 offset:8704
	ds_read_b128 v[196:199], v118 offset:8720
	ds_read_b128 v[184:187], v118 offset:33280
	ds_read_b128 v[188:191], v118 offset:33296
	s_waitcnt lgkmcnt(4)
	v_pk_mul_f32 v[30:31], v[206:207], v[156:157] op_sel_hi:[1,0]
	v_pk_mul_f32 v[32:33], v[208:209], v[156:157] op_sel_hi:[1,0]
	v_pk_mul_f32 v[34:35], v[210:211], v[156:157] op_sel_hi:[1,0]
	v_pk_mul_f32 v[36:37], v[212:213], v[156:157] op_sel_hi:[1,0]
	ds_read_b128 v[214:217], v118 offset:512
	ds_read_b128 v[218:221], v118 offset:528
	v_pk_mul_f32 v[38:39], v[84:85], v[176:177]
	v_pk_mul_f32 v[40:41], v[84:85], v[146:147]
	v_pk_fma_f32 v[38:39], v[86:87], v[178:179], v[38:39]
	v_pk_fma_f32 v[40:41], v[86:87], v[148:149], v[40:41]
	v_pk_fma_f32 v[38:39], v[88:89], v[180:181], v[38:39]
	v_pk_fma_f32 v[40:41], v[88:89], v[150:151], v[40:41]
	v_pk_fma_f32 v[38:39], v[90:91], v[182:183], v[38:39]
	v_pk_fma_f32 v[40:41], v[90:91], v[152:153], v[40:41]
	ds_read_b128 v[222:225], v118 offset:25344
	ds_read_b128 v[226:229], v118 offset:25360
	v_add_f32_e32 v42, v38, v39
	v_add_f32_e32 v44, v40, v41
	s_waitcnt lgkmcnt(7)
	v_pk_fma_f32 v[30:31], v[84:85], v[192:193], v[30:31]
	v_add_f32_dpp v42, v42, v42 quad_perm:[1,0,3,2] row_mask:0xf bank_mask:0xf bound_ctrl:1
	v_add_f32_dpp v44, v44, v44 quad_perm:[1,0,3,2] row_mask:0xf bank_mask:0xf bound_ctrl:1
	v_pk_fma_f32 v[32:33], v[86:87], v[194:195], v[32:33]
	v_add_f32_dpp v42, v42, v42 quad_perm:[2,3,0,1] row_mask:0xf bank_mask:0xf bound_ctrl:1
	v_add_f32_dpp v44, v44, v44 quad_perm:[2,3,0,1] row_mask:0xf bank_mask:0xf bound_ctrl:1
	s_waitcnt lgkmcnt(6)
	v_pk_fma_f32 v[34:35], v[88:89], v[196:197], v[34:35]
	v_add_f32_dpp v42, v42, v42 row_half_mirror row_mask:0xf bank_mask:0xf bound_ctrl:1
	v_add_f32_dpp v46, v44, v44 row_half_mirror row_mask:0xf bank_mask:0xf bound_ctrl:1
	v_pk_fma_f32 v[36:37], v[90:91], v[198:199], v[36:37]
	ds_read_b128 v[130:133], v118 offset:17152
	ds_read_b128 v[134:137], v118 offset:17168
	s_waitcnt lgkmcnt(7)
	v_pk_fma_f32 v[84:85], v[184:185], v[42:43], v[30:31] op_sel_hi:[1,0,1]
	v_pk_fma_f32 v[86:87], v[186:187], v[42:43], v[32:33] op_sel_hi:[1,0,1]
	s_waitcnt lgkmcnt(6)
	v_pk_fma_f32 v[88:89], v[188:189], v[42:43], v[34:35] op_sel_hi:[1,0,1]
	v_pk_fma_f32 v[90:91], v[190:191], v[42:43], v[36:37] op_sel_hi:[1,0,1]
	ds_read_b128 v[122:125], v118 offset:8960
	ds_read_b128 v[126:129], v118 offset:8976
	ds_read_b128 v[230:233], v118 offset:33536
	ds_read_b128 v[234:237], v118 offset:33552
	s_waitcnt lgkmcnt(4)
	v_pk_mul_f32 v[30:31], v[130:131], v[156:157] op_sel:[0,1]
	v_pk_mul_f32 v[32:33], v[132:133], v[156:157] op_sel:[0,1]
	v_pk_mul_f32 v[34:35], v[134:135], v[156:157] op_sel:[0,1]
	v_pk_mul_f32 v[36:37], v[136:137], v[156:157] op_sel:[0,1]
	ds_read_b128 v[146:149], v118 offset:768
	ds_read_b128 v[150:153], v118 offset:784
	v_pk_mul_f32 v[38:39], v[84:85], v[222:223]
	v_pk_mul_f32 v[40:41], v[84:85], v[214:215]
	v_pk_fma_f32 v[38:39], v[86:87], v[224:225], v[38:39]
	v_pk_fma_f32 v[40:41], v[86:87], v[216:217], v[40:41]
	v_pk_fma_f32 v[38:39], v[88:89], v[226:227], v[38:39]
	v_pk_fma_f32 v[40:41], v[88:89], v[218:219], v[40:41]
	v_pk_fma_f32 v[38:39], v[90:91], v[228:229], v[38:39]
	v_pk_fma_f32 v[40:41], v[90:91], v[220:221], v[40:41]
	ds_read_b128 v[176:179], v118 offset:25600
	ds_read_b128 v[180:183], v118 offset:25616
	v_add_f32_e32 v42, v38, v39
	v_add_f32_e32 v44, v40, v41
	s_waitcnt lgkmcnt(7)
	v_pk_fma_f32 v[30:31], v[84:85], v[122:123], v[30:31]
	v_add_f32_dpp v42, v42, v42 quad_perm:[1,0,3,2] row_mask:0xf bank_mask:0xf bound_ctrl:1
	v_add_f32_dpp v44, v44, v44 quad_perm:[1,0,3,2] row_mask:0xf bank_mask:0xf bound_ctrl:1
	v_pk_fma_f32 v[32:33], v[86:87], v[124:125], v[32:33]
	v_add_f32_dpp v42, v42, v42 quad_perm:[2,3,0,1] row_mask:0xf bank_mask:0xf bound_ctrl:1
	v_add_f32_dpp v44, v44, v44 quad_perm:[2,3,0,1] row_mask:0xf bank_mask:0xf bound_ctrl:1
	s_waitcnt lgkmcnt(6)
	v_pk_fma_f32 v[34:35], v[88:89], v[126:127], v[34:35]
	v_add_f32_dpp v42, v42, v42 row_half_mirror row_mask:0xf bank_mask:0xf bound_ctrl:1
	v_add_f32_dpp v47, v44, v44 row_half_mirror row_mask:0xf bank_mask:0xf bound_ctrl:1
	v_pk_fma_f32 v[36:37], v[90:91], v[128:129], v[36:37]
	ds_read_b128 v[206:209], v118 offset:17408
	ds_read_b128 v[210:213], v118 offset:17424
	s_waitcnt lgkmcnt(7)
	v_pk_fma_f32 v[84:85], v[230:231], v[42:43], v[30:31] op_sel_hi:[1,0,1]
	v_pk_fma_f32 v[86:87], v[232:233], v[42:43], v[32:33] op_sel_hi:[1,0,1]
	s_waitcnt lgkmcnt(6)
	v_pk_fma_f32 v[88:89], v[234:235], v[42:43], v[34:35] op_sel_hi:[1,0,1]
	v_pk_fma_f32 v[90:91], v[236:237], v[42:43], v[36:37] op_sel_hi:[1,0,1]
	ds_read_b128 v[192:195], v118 offset:9216
	ds_read_b128 v[196:199], v118 offset:9232
	ds_read_b128 v[184:187], v118 offset:33792
	ds_read_b128 v[188:191], v118 offset:33808
	s_waitcnt lgkmcnt(4)
	v_pk_mul_f32 v[30:31], v[206:207], v[158:159] op_sel_hi:[1,0]
	v_pk_mul_f32 v[32:33], v[208:209], v[158:159] op_sel_hi:[1,0]
	v_pk_mul_f32 v[34:35], v[210:211], v[158:159] op_sel_hi:[1,0]
	v_pk_mul_f32 v[36:37], v[212:213], v[158:159] op_sel_hi:[1,0]
	ds_read_b128 v[214:217], v118 offset:1024
	ds_read_b128 v[218:221], v118 offset:1040
	v_pk_mul_f32 v[38:39], v[84:85], v[176:177]
	v_pk_mul_f32 v[40:41], v[84:85], v[146:147]
	v_pk_fma_f32 v[38:39], v[86:87], v[178:179], v[38:39]
	v_pk_fma_f32 v[40:41], v[86:87], v[148:149], v[40:41]
	v_pk_fma_f32 v[38:39], v[88:89], v[180:181], v[38:39]
	v_pk_fma_f32 v[40:41], v[88:89], v[150:151], v[40:41]
	v_pk_fma_f32 v[38:39], v[90:91], v[182:183], v[38:39]
	v_pk_fma_f32 v[40:41], v[90:91], v[152:153], v[40:41]
	ds_read_b128 v[222:225], v118 offset:25856
	ds_read_b128 v[226:229], v118 offset:25872
	v_add_f32_e32 v42, v38, v39
	v_add_f32_e32 v44, v40, v41
	s_waitcnt lgkmcnt(7)
	v_pk_fma_f32 v[30:31], v[84:85], v[192:193], v[30:31]
	v_add_f32_dpp v42, v42, v42 quad_perm:[1,0,3,2] row_mask:0xf bank_mask:0xf bound_ctrl:1
	v_add_f32_dpp v44, v44, v44 quad_perm:[1,0,3,2] row_mask:0xf bank_mask:0xf bound_ctrl:1
	v_pk_fma_f32 v[32:33], v[86:87], v[194:195], v[32:33]
	v_add_f32_dpp v42, v42, v42 quad_perm:[2,3,0,1] row_mask:0xf bank_mask:0xf bound_ctrl:1
	v_add_f32_dpp v44, v44, v44 quad_perm:[2,3,0,1] row_mask:0xf bank_mask:0xf bound_ctrl:1
	s_waitcnt lgkmcnt(6)
	v_pk_fma_f32 v[34:35], v[88:89], v[196:197], v[34:35]
	v_add_f32_dpp v42, v42, v42 row_half_mirror row_mask:0xf bank_mask:0xf bound_ctrl:1
	v_add_f32_dpp v48, v44, v44 row_half_mirror row_mask:0xf bank_mask:0xf bound_ctrl:1
	v_pk_fma_f32 v[36:37], v[90:91], v[198:199], v[36:37]
	ds_read_b128 v[130:133], v118 offset:17664
	ds_read_b128 v[134:137], v118 offset:17680
	s_waitcnt lgkmcnt(7)
	v_pk_fma_f32 v[84:85], v[184:185], v[42:43], v[30:31] op_sel_hi:[1,0,1]
	v_pk_fma_f32 v[86:87], v[186:187], v[42:43], v[32:33] op_sel_hi:[1,0,1]
	s_waitcnt lgkmcnt(6)
	v_pk_fma_f32 v[88:89], v[188:189], v[42:43], v[34:35] op_sel_hi:[1,0,1]
	v_pk_fma_f32 v[90:91], v[190:191], v[42:43], v[36:37] op_sel_hi:[1,0,1]
	ds_read_b128 v[122:125], v118 offset:9472
	ds_read_b128 v[126:129], v118 offset:9488
	ds_read_b128 v[230:233], v118 offset:34048
	ds_read_b128 v[234:237], v118 offset:34064
	s_waitcnt lgkmcnt(4)
	v_pk_mul_f32 v[30:31], v[130:131], v[158:159] op_sel:[0,1]
	v_pk_mul_f32 v[32:33], v[132:133], v[158:159] op_sel:[0,1]
	v_pk_mul_f32 v[34:35], v[134:135], v[158:159] op_sel:[0,1]
	v_pk_mul_f32 v[36:37], v[136:137], v[158:159] op_sel:[0,1]
	ds_read_b128 v[146:149], v118 offset:1280
	ds_read_b128 v[150:153], v118 offset:1296
	v_pk_mul_f32 v[38:39], v[84:85], v[222:223]
	v_pk_mul_f32 v[40:41], v[84:85], v[214:215]
	v_pk_fma_f32 v[38:39], v[86:87], v[224:225], v[38:39]
	v_pk_fma_f32 v[40:41], v[86:87], v[216:217], v[40:41]
	v_pk_fma_f32 v[38:39], v[88:89], v[226:227], v[38:39]
	v_pk_fma_f32 v[40:41], v[88:89], v[218:219], v[40:41]
	v_pk_fma_f32 v[38:39], v[90:91], v[228:229], v[38:39]
	v_pk_fma_f32 v[40:41], v[90:91], v[220:221], v[40:41]
	ds_read_b128 v[176:179], v118 offset:26112
	ds_read_b128 v[180:183], v118 offset:26128
	v_add_f32_e32 v42, v38, v39
	v_add_f32_e32 v44, v40, v41
	s_waitcnt lgkmcnt(7)
	v_pk_fma_f32 v[30:31], v[84:85], v[122:123], v[30:31]
	v_add_f32_dpp v42, v42, v42 quad_perm:[1,0,3,2] row_mask:0xf bank_mask:0xf bound_ctrl:1
	v_add_f32_dpp v44, v44, v44 quad_perm:[1,0,3,2] row_mask:0xf bank_mask:0xf bound_ctrl:1
	v_pk_fma_f32 v[32:33], v[86:87], v[124:125], v[32:33]
	v_add_f32_dpp v42, v42, v42 quad_perm:[2,3,0,1] row_mask:0xf bank_mask:0xf bound_ctrl:1
	v_add_f32_dpp v44, v44, v44 quad_perm:[2,3,0,1] row_mask:0xf bank_mask:0xf bound_ctrl:1
	s_waitcnt lgkmcnt(6)
	v_pk_fma_f32 v[34:35], v[88:89], v[126:127], v[34:35]
	v_add_f32_dpp v42, v42, v42 row_half_mirror row_mask:0xf bank_mask:0xf bound_ctrl:1
	v_add_f32_dpp v49, v44, v44 row_half_mirror row_mask:0xf bank_mask:0xf bound_ctrl:1
	v_pk_fma_f32 v[36:37], v[90:91], v[128:129], v[36:37]
	ds_read_b128 v[206:209], v118 offset:17920
	ds_read_b128 v[210:213], v118 offset:17936
	s_waitcnt lgkmcnt(7)
	v_pk_fma_f32 v[84:85], v[230:231], v[42:43], v[30:31] op_sel_hi:[1,0,1]
	v_pk_fma_f32 v[86:87], v[232:233], v[42:43], v[32:33] op_sel_hi:[1,0,1]
	s_waitcnt lgkmcnt(6)
	v_pk_fma_f32 v[88:89], v[234:235], v[42:43], v[34:35] op_sel_hi:[1,0,1]
	v_pk_fma_f32 v[90:91], v[236:237], v[42:43], v[36:37] op_sel_hi:[1,0,1]
	ds_read_b128 v[192:195], v118 offset:9728
	ds_read_b128 v[196:199], v118 offset:9744
	ds_read_b128 v[184:187], v118 offset:34304
	ds_read_b128 v[188:191], v118 offset:34320
	s_waitcnt lgkmcnt(4)
	v_pk_mul_f32 v[30:31], v[206:207], v[238:239] op_sel_hi:[1,0]
	v_pk_mul_f32 v[32:33], v[208:209], v[238:239] op_sel_hi:[1,0]
	v_pk_mul_f32 v[34:35], v[210:211], v[238:239] op_sel_hi:[1,0]
	v_pk_mul_f32 v[36:37], v[212:213], v[238:239] op_sel_hi:[1,0]
	ds_read_b128 v[214:217], v118 offset:1536
	ds_read_b128 v[218:221], v118 offset:1552
	v_pk_mul_f32 v[38:39], v[84:85], v[176:177]
	v_pk_mul_f32 v[40:41], v[84:85], v[146:147]
	v_pk_fma_f32 v[38:39], v[86:87], v[178:179], v[38:39]
	v_pk_fma_f32 v[40:41], v[86:87], v[148:149], v[40:41]
	v_pk_fma_f32 v[38:39], v[88:89], v[180:181], v[38:39]
	v_pk_fma_f32 v[40:41], v[88:89], v[150:151], v[40:41]
	v_pk_fma_f32 v[38:39], v[90:91], v[182:183], v[38:39]
	v_pk_fma_f32 v[40:41], v[90:91], v[152:153], v[40:41]
	ds_read_b128 v[222:225], v118 offset:26368
	ds_read_b128 v[226:229], v118 offset:26384
	v_add_f32_e32 v42, v38, v39
	v_add_f32_e32 v44, v40, v41
	s_waitcnt lgkmcnt(7)
	v_pk_fma_f32 v[30:31], v[84:85], v[192:193], v[30:31]
	v_add_f32_dpp v42, v42, v42 quad_perm:[1,0,3,2] row_mask:0xf bank_mask:0xf bound_ctrl:1
	v_add_f32_dpp v44, v44, v44 quad_perm:[1,0,3,2] row_mask:0xf bank_mask:0xf bound_ctrl:1
	v_pk_fma_f32 v[32:33], v[86:87], v[194:195], v[32:33]
	v_add_f32_dpp v42, v42, v42 quad_perm:[2,3,0,1] row_mask:0xf bank_mask:0xf bound_ctrl:1
	v_add_f32_dpp v44, v44, v44 quad_perm:[2,3,0,1] row_mask:0xf bank_mask:0xf bound_ctrl:1
	s_waitcnt lgkmcnt(6)
	v_pk_fma_f32 v[34:35], v[88:89], v[196:197], v[34:35]
	v_add_f32_dpp v42, v42, v42 row_half_mirror row_mask:0xf bank_mask:0xf bound_ctrl:1
	v_add_f32_dpp v200, v44, v44 row_half_mirror row_mask:0xf bank_mask:0xf bound_ctrl:1
	v_pk_fma_f32 v[36:37], v[90:91], v[198:199], v[36:37]
	ds_read_b128 v[130:133], v118 offset:18176
	ds_read_b128 v[134:137], v118 offset:18192
	s_waitcnt lgkmcnt(7)
	v_pk_fma_f32 v[84:85], v[184:185], v[42:43], v[30:31] op_sel_hi:[1,0,1]
	v_pk_fma_f32 v[86:87], v[186:187], v[42:43], v[32:33] op_sel_hi:[1,0,1]
	s_waitcnt lgkmcnt(6)
	v_pk_fma_f32 v[88:89], v[188:189], v[42:43], v[34:35] op_sel_hi:[1,0,1]
	v_pk_fma_f32 v[90:91], v[190:191], v[42:43], v[36:37] op_sel_hi:[1,0,1]
	ds_read_b128 v[122:125], v118 offset:9984
	ds_read_b128 v[126:129], v118 offset:10000
	ds_read_b128 v[230:233], v118 offset:34560
	ds_read_b128 v[234:237], v118 offset:34576
	s_waitcnt lgkmcnt(4)
	v_pk_mul_f32 v[30:31], v[130:131], v[238:239] op_sel:[0,1]
	v_pk_mul_f32 v[32:33], v[132:133], v[238:239] op_sel:[0,1]
	v_pk_mul_f32 v[34:35], v[134:135], v[238:239] op_sel:[0,1]
	v_pk_mul_f32 v[36:37], v[136:137], v[238:239] op_sel:[0,1]
	ds_read_b128 v[146:149], v118 offset:1792
	ds_read_b128 v[150:153], v118 offset:1808
	v_pk_mul_f32 v[38:39], v[84:85], v[222:223]
	v_pk_mul_f32 v[40:41], v[84:85], v[214:215]
	v_pk_fma_f32 v[38:39], v[86:87], v[224:225], v[38:39]
	v_pk_fma_f32 v[40:41], v[86:87], v[216:217], v[40:41]
	v_pk_fma_f32 v[38:39], v[88:89], v[226:227], v[38:39]
	v_pk_fma_f32 v[40:41], v[88:89], v[218:219], v[40:41]
	v_pk_fma_f32 v[38:39], v[90:91], v[228:229], v[38:39]
	v_pk_fma_f32 v[40:41], v[90:91], v[220:221], v[40:41]
	v_add_f32_e32 v42, v38, v39
	v_add_f32_e32 v44, v40, v41
	s_waitcnt lgkmcnt(5)
	v_pk_fma_f32 v[30:31], v[84:85], v[122:123], v[30:31]
	v_add_f32_dpp v42, v42, v42 quad_perm:[1,0,3,2] row_mask:0xf bank_mask:0xf bound_ctrl:1
	v_add_f32_dpp v44, v44, v44 quad_perm:[1,0,3,2] row_mask:0xf bank_mask:0xf bound_ctrl:1
	v_pk_fma_f32 v[32:33], v[86:87], v[124:125], v[32:33]
	v_add_f32_dpp v42, v42, v42 quad_perm:[2,3,0,1] row_mask:0xf bank_mask:0xf bound_ctrl:1
	v_add_f32_dpp v44, v44, v44 quad_perm:[2,3,0,1] row_mask:0xf bank_mask:0xf bound_ctrl:1
	s_waitcnt lgkmcnt(4)
	v_pk_fma_f32 v[34:35], v[88:89], v[126:127], v[34:35]
	v_add_f32_dpp v42, v42, v42 row_half_mirror row_mask:0xf bank_mask:0xf bound_ctrl:1
	v_add_f32_dpp v201, v44, v44 row_half_mirror row_mask:0xf bank_mask:0xf bound_ctrl:1
	v_pk_fma_f32 v[36:37], v[90:91], v[128:129], v[36:37]
	s_waitcnt lgkmcnt(3)
	v_pk_fma_f32 v[84:85], v[230:231], v[42:43], v[30:31] op_sel_hi:[1,0,1]
	v_pk_fma_f32 v[86:87], v[232:233], v[42:43], v[32:33] op_sel_hi:[1,0,1]
	s_waitcnt lgkmcnt(2)
	v_pk_fma_f32 v[88:89], v[234:235], v[42:43], v[34:35] op_sel_hi:[1,0,1]
	v_pk_fma_f32 v[90:91], v[236:237], v[42:43], v[36:37] op_sel_hi:[1,0,1]
	s_waitcnt lgkmcnt(1)
	v_pk_mul_f32 v[40:41], v[84:85], v[146:147]
	v_pk_fma_f32 v[40:41], v[86:87], v[148:149], v[40:41]
	s_waitcnt lgkmcnt(0)
	v_pk_fma_f32 v[40:41], v[88:89], v[150:151], v[40:41]
	v_pk_fma_f32 v[40:41], v[90:91], v[152:153], v[40:41]
	v_add_f32_e32 v44, v40, v41
	s_nop 1
	v_add_f32_dpp v44, v44, v44 quad_perm:[1,0,3,2] row_mask:0xf bank_mask:0xf bound_ctrl:1
	s_nop 1
	v_add_f32_dpp v44, v44, v44 quad_perm:[2,3,0,1] row_mask:0xf bank_mask:0xf bound_ctrl:1
	s_nop 1
	v_add_f32_dpp v202, v44, v44 row_half_mirror row_mask:0xf bank_mask:0xf bound_ctrl:1
	s_and_saveexec_b64 s[46:47], s[12:13]
	ds_write_b32 v240, v45 offset:0
	ds_write_b32 v240, v46 offset:128
	ds_write_b32 v240, v47 offset:256
	ds_write_b32 v240, v48 offset:384
	ds_write_b32 v240, v49 offset:512
	ds_write_b32 v240, v200 offset:640
	ds_write_b32 v240, v201 offset:768
	ds_write_b32 v240, v202 offset:896
.LBB0_174:
	s_or_b64 exec, exec, s[46:47]
	s_setprio 0
